# gdn_g1 A-matrix dot loops: the 16 LDS reads of each unrolled step issued together with counted lgkmcnt waits (same fmac order) instead of a wait per read pair
# speedup vs baseline: 1.0095x; 1.0095x over previous
; DI void gdn_g1(const Params& p, int l, int ch, char* smem) {
;     ...
;   for (int i = 0; i < 16; ++i) { const int s = part + 4 * i; float a = 0.f;
;     if (s < c) { float dot = 0.f;
; #pragma unroll 16
;       for (int d = 0; d < 64; ++d) dot += sR[c * 129 + 64 + d] * sR[s * 129 + 64 + d];
;       a = bc * dot * expf(Gc - sG[s]); }
;     sA[c * 64 + s] = a; }
.LBB0_598:
	v_add_u32_e32 v12, s2, v5
	v_add_u32_e32 v13, s2, v7
	ds_read2_b32 v[114:115], v12 offset1:1
	ds_read2_b32 v[116:117], v13 offset1:1
	ds_read2_b32 v[118:119], v12 offset0:2 offset1:3
	ds_read2_b32 v[120:121], v13 offset0:2 offset1:3
	ds_read2_b32 v[122:123], v12 offset0:4 offset1:5
	ds_read2_b32 v[124:125], v13 offset0:4 offset1:5
	ds_read2_b32 v[126:127], v12 offset0:6 offset1:7
	ds_read2_b32 v[128:129], v13 offset0:6 offset1:7
	ds_read2_b32 v[130:131], v12 offset0:8 offset1:9
	ds_read2_b32 v[132:133], v13 offset0:8 offset1:9
	ds_read2_b32 v[134:135], v12 offset0:10 offset1:11
	ds_read2_b32 v[136:137], v13 offset0:10 offset1:11
	ds_read2_b32 v[138:139], v12 offset0:12 offset1:13
	ds_read2_b32 v[146:147], v13 offset0:12 offset1:13
	s_add_i32 s2, s2, 64
	s_cmpk_eq_i32 s2, 0x100
	s_waitcnt lgkmcnt(12)
	v_fmac_f32_e32 v6, v114, v116
	v_fmac_f32_e32 v6, v115, v117
	ds_read2_b32 v[148:149], v12 offset0:14 offset1:15
	ds_read2_b32 v[150:151], v13 offset0:14 offset1:15
	s_waitcnt lgkmcnt(12)
	v_fmac_f32_e32 v6, v118, v120
	v_fmac_f32_e32 v6, v119, v121
	s_waitcnt lgkmcnt(10)
	v_fmac_f32_e32 v6, v122, v124
	v_fmac_f32_e32 v6, v123, v125
	s_waitcnt lgkmcnt(8)
	v_fmac_f32_e32 v6, v126, v128
	v_fmac_f32_e32 v6, v127, v129
	s_waitcnt lgkmcnt(6)
	v_fmac_f32_e32 v6, v130, v132
	v_fmac_f32_e32 v6, v131, v133
	s_waitcnt lgkmcnt(4)
	v_fmac_f32_e32 v6, v134, v136
	v_fmac_f32_e32 v6, v135, v137
	s_waitcnt lgkmcnt(2)
	v_fmac_f32_e32 v6, v138, v146
	v_fmac_f32_e32 v6, v139, v147
	s_waitcnt lgkmcnt(0)
	v_fmac_f32_e32 v6, v148, v150
	v_fmac_f32_e32 v6, v149, v151
	s_cbranch_scc0 .LBB0_598
	v_lshlrev_b32_e32 v7, 2, v93
	ds_read_b32 v7, v7 offset:49408
	s_mov_b32 s2, 0x3fb8aa3b
	v_mul_f32_e32 v6, v3, v6
	s_waitcnt lgkmcnt(0)
	v_sub_f32_e32 v7, v2, v7
	v_mul_f32_e32 v8, 0x3fb8aa3b, v7
	v_fma_f32 v9, v7, s2, -v8
	v_rndne_f32_e32 v10, v8
	v_fmac_f32_e32 v9, 0x32a5705f, v7
	v_sub_f32_e32 v8, v8, v10
	v_add_f32_e32 v8, v8, v9
	v_cvt_i32_f32_e32 v10, v10
	v_exp_f32_e32 v8, v8
	s_mov_b32 s2, 0xc2ce8ed0
	v_cmp_ngt_f32_e32 vcc, s2, v7
	s_mov_b32 s2, 0x42b17218
	v_ldexp_f32 v8, v8, v10
	v_cndmask_b32_e32 v8, 0, v8, vcc
	v_cmp_nlt_f32_e32 vcc, s2, v7
	s_nop 1
	v_cndmask_b32_e32 v7, v187, v8, vcc
	v_mul_f32_e32 v95, v6, v7

; DI void gdn_g1(const Params& p, int l, int ch, char* smem) {
;     ...
;   for (int i = 0; i < 16; ++i) { const int s = part + 4 * i; float a = 0.f;
;     if (s < c) { float dot = 0.f;
; #pragma unroll 16
;       for (int d = 0; d < 64; ++d) dot += sR[c * 129 + 64 + d] * sR[s * 129 + 64 + d];
;       a = bc * dot * expf(Gc - sG[s]); }
;     sA[c * 64 + s] = a; }
.LBB0_602:
	v_add_u32_e32 v14, s2, v5
	v_add_u32_e32 v15, s2, v9
	ds_read2_b32 v[114:115], v14 offset1:1
	ds_read2_b32 v[116:117], v15 offset1:1
	ds_read2_b32 v[118:119], v14 offset0:2 offset1:3
	ds_read2_b32 v[120:121], v15 offset0:2 offset1:3
	ds_read2_b32 v[122:123], v14 offset0:4 offset1:5
	ds_read2_b32 v[124:125], v15 offset0:4 offset1:5
	ds_read2_b32 v[126:127], v14 offset0:6 offset1:7
	ds_read2_b32 v[128:129], v15 offset0:6 offset1:7
	ds_read2_b32 v[130:131], v14 offset0:8 offset1:9
	ds_read2_b32 v[132:133], v15 offset0:8 offset1:9
	ds_read2_b32 v[134:135], v14 offset0:10 offset1:11
	ds_read2_b32 v[136:137], v15 offset0:10 offset1:11
	ds_read2_b32 v[138:139], v14 offset0:12 offset1:13
	ds_read2_b32 v[146:147], v15 offset0:12 offset1:13
	s_add_i32 s2, s2, 64
	s_cmpk_lg_i32 s2, 0x100
	s_waitcnt lgkmcnt(12)
	v_fmac_f32_e32 v8, v114, v116
	v_fmac_f32_e32 v8, v115, v117
	ds_read2_b32 v[148:149], v14 offset0:14 offset1:15
	ds_read2_b32 v[150:151], v15 offset0:14 offset1:15
	s_waitcnt lgkmcnt(12)
	v_fmac_f32_e32 v8, v118, v120
	v_fmac_f32_e32 v8, v119, v121
	s_waitcnt lgkmcnt(10)
	v_fmac_f32_e32 v8, v122, v124
	v_fmac_f32_e32 v8, v123, v125
	s_waitcnt lgkmcnt(8)
	v_fmac_f32_e32 v8, v126, v128
	v_fmac_f32_e32 v8, v127, v129
	s_waitcnt lgkmcnt(6)
	v_fmac_f32_e32 v8, v130, v132
	v_fmac_f32_e32 v8, v131, v133
	s_waitcnt lgkmcnt(4)
	v_fmac_f32_e32 v8, v134, v136
	v_fmac_f32_e32 v8, v135, v137
	s_waitcnt lgkmcnt(2)
	v_fmac_f32_e32 v8, v138, v146
	v_fmac_f32_e32 v8, v139, v147
	s_waitcnt lgkmcnt(0)
	v_fmac_f32_e32 v8, v148, v150
	v_fmac_f32_e32 v8, v149, v151
	s_cbranch_scc1 .LBB0_602
	ds_read_b32 v9, v7 offset:49424
	s_mov_b32 s2, 0x3fb8aa3b
	v_mul_f32_e32 v8, v3, v8
	s_waitcnt lgkmcnt(0)
	v_sub_f32_e32 v9, v2, v9
	v_mul_f32_e32 v10, 0x3fb8aa3b, v9
	v_fma_f32 v11, v9, s2, -v10
	v_rndne_f32_e32 v12, v10
	v_fmac_f32_e32 v11, 0x32a5705f, v9
	v_sub_f32_e32 v10, v10, v12
	v_add_f32_e32 v10, v10, v11
	v_cvt_i32_f32_e32 v12, v12
	v_exp_f32_e32 v10, v10
	s_mov_b32 s2, 0xc2ce8ed0
	v_cmp_ngt_f32_e32 vcc, s2, v9
	s_mov_b32 s2, 0x42b17218
	v_ldexp_f32 v10, v10, v12
	v_cndmask_b32_e32 v10, 0, v10, vcc
	v_cmp_nlt_f32_e32 vcc, s2, v9
	s_nop 1
	v_cndmask_b32_e32 v9, v187, v10, vcc
	v_mul_f32_e32 v8, v8, v9

; DI void gdn_g1(const Params& p, int l, int ch, char* smem) {
;     ...
;   for (int i = 0; i < 16; ++i) { const int s = part + 4 * i; float a = 0.f;
;     if (s < c) { float dot = 0.f;
; #pragma unroll 16
;       for (int d = 0; d < 64; ++d) dot += sR[c * 129 + 64 + d] * sR[s * 129 + 64 + d];
;       a = bc * dot * expf(Gc - sG[s]); }
;     sA[c * 64 + s] = a; }
.LBB0_606:
	v_add_u32_e32 v14, s2, v5
	v_add_u32_e32 v15, s2, v9
	ds_read2_b32 v[114:115], v14 offset1:1
	ds_read2_b32 v[116:117], v15 offset1:1
	ds_read2_b32 v[118:119], v14 offset0:2 offset1:3
	ds_read2_b32 v[120:121], v15 offset0:2 offset1:3
	ds_read2_b32 v[122:123], v14 offset0:4 offset1:5
	ds_read2_b32 v[124:125], v15 offset0:4 offset1:5
	ds_read2_b32 v[126:127], v14 offset0:6 offset1:7
	ds_read2_b32 v[128:129], v15 offset0:6 offset1:7
	ds_read2_b32 v[130:131], v14 offset0:8 offset1:9
	ds_read2_b32 v[132:133], v15 offset0:8 offset1:9
	ds_read2_b32 v[134:135], v14 offset0:10 offset1:11
	ds_read2_b32 v[136:137], v15 offset0:10 offset1:11
	ds_read2_b32 v[138:139], v14 offset0:12 offset1:13
	ds_read2_b32 v[146:147], v15 offset0:12 offset1:13
	s_add_i32 s2, s2, 64
	s_cmpk_lg_i32 s2, 0x100
	s_waitcnt lgkmcnt(12)
	v_fmac_f32_e32 v8, v114, v116
	v_fmac_f32_e32 v8, v115, v117
	ds_read2_b32 v[148:149], v14 offset0:14 offset1:15
	ds_read2_b32 v[150:151], v15 offset0:14 offset1:15
	s_waitcnt lgkmcnt(12)
	v_fmac_f32_e32 v8, v118, v120
	v_fmac_f32_e32 v8, v119, v121
	s_waitcnt lgkmcnt(10)
	v_fmac_f32_e32 v8, v122, v124
	v_fmac_f32_e32 v8, v123, v125
	s_waitcnt lgkmcnt(8)
	v_fmac_f32_e32 v8, v126, v128
	v_fmac_f32_e32 v8, v127, v129
	s_waitcnt lgkmcnt(6)
	v_fmac_f32_e32 v8, v130, v132
	v_fmac_f32_e32 v8, v131, v133
	s_waitcnt lgkmcnt(4)
	v_fmac_f32_e32 v8, v134, v136
	v_fmac_f32_e32 v8, v135, v137
	s_waitcnt lgkmcnt(2)
	v_fmac_f32_e32 v8, v138, v146
	v_fmac_f32_e32 v8, v139, v147
	s_waitcnt lgkmcnt(0)
	v_fmac_f32_e32 v8, v148, v150
	v_fmac_f32_e32 v8, v149, v151
	s_cbranch_scc1 .LBB0_606
	ds_read_b32 v9, v7 offset:49440
	s_mov_b32 s2, 0x3fb8aa3b
	v_mul_f32_e32 v8, v3, v8
	s_waitcnt lgkmcnt(0)
	v_sub_f32_e32 v9, v2, v9
	v_mul_f32_e32 v10, 0x3fb8aa3b, v9
	v_fma_f32 v11, v9, s2, -v10
	v_rndne_f32_e32 v12, v10
	v_fmac_f32_e32 v11, 0x32a5705f, v9
	v_sub_f32_e32 v10, v10, v12
	v_add_f32_e32 v10, v10, v11
	v_cvt_i32_f32_e32 v12, v12
	v_exp_f32_e32 v10, v10
	s_mov_b32 s2, 0xc2ce8ed0
	v_cmp_ngt_f32_e32 vcc, s2, v9
	s_mov_b32 s2, 0x42b17218
	v_ldexp_f32 v10, v10, v12
	v_cndmask_b32_e32 v10, 0, v10, vcc
	v_cmp_nlt_f32_e32 vcc, s2, v9
	s_nop 1
	v_cndmask_b32_e32 v9, v187, v10, vcc
	v_mul_f32_e32 v8, v8, v9

; DI void gdn_g1(const Params& p, int l, int ch, char* smem) {
;     ...
;   for (int i = 0; i < 16; ++i) { const int s = part + 4 * i; float a = 0.f;
;     if (s < c) { float dot = 0.f;
; #pragma unroll 16
;       for (int d = 0; d < 64; ++d) dot += sR[c * 129 + 64 + d] * sR[s * 129 + 64 + d];
;       a = bc * dot * expf(Gc - sG[s]); }
;     sA[c * 64 + s] = a; }
.LBB0_610:
	v_add_u32_e32 v14, s2, v5
	v_add_u32_e32 v15, s2, v9
	ds_read2_b32 v[114:115], v14 offset1:1
	ds_read2_b32 v[116:117], v15 offset1:1
	ds_read2_b32 v[118:119], v14 offset0:2 offset1:3
	ds_read2_b32 v[120:121], v15 offset0:2 offset1:3
	ds_read2_b32 v[122:123], v14 offset0:4 offset1:5
	ds_read2_b32 v[124:125], v15 offset0:4 offset1:5
	ds_read2_b32 v[126:127], v14 offset0:6 offset1:7
	ds_read2_b32 v[128:129], v15 offset0:6 offset1:7
	ds_read2_b32 v[130:131], v14 offset0:8 offset1:9
	ds_read2_b32 v[132:133], v15 offset0:8 offset1:9
	ds_read2_b32 v[134:135], v14 offset0:10 offset1:11
	ds_read2_b32 v[136:137], v15 offset0:10 offset1:11
	ds_read2_b32 v[138:139], v14 offset0:12 offset1:13
	ds_read2_b32 v[146:147], v15 offset0:12 offset1:13
	s_add_i32 s2, s2, 64
	s_cmpk_lg_i32 s2, 0x100
	s_waitcnt lgkmcnt(12)
	v_fmac_f32_e32 v8, v114, v116
	v_fmac_f32_e32 v8, v115, v117
	ds_read2_b32 v[148:149], v14 offset0:14 offset1:15
	ds_read2_b32 v[150:151], v15 offset0:14 offset1:15
	s_waitcnt lgkmcnt(12)
	v_fmac_f32_e32 v8, v118, v120
	v_fmac_f32_e32 v8, v119, v121
	s_waitcnt lgkmcnt(10)
	v_fmac_f32_e32 v8, v122, v124
	v_fmac_f32_e32 v8, v123, v125
	s_waitcnt lgkmcnt(8)
	v_fmac_f32_e32 v8, v126, v128
	v_fmac_f32_e32 v8, v127, v129
	s_waitcnt lgkmcnt(6)
	v_fmac_f32_e32 v8, v130, v132
	v_fmac_f32_e32 v8, v131, v133
	s_waitcnt lgkmcnt(4)
	v_fmac_f32_e32 v8, v134, v136
	v_fmac_f32_e32 v8, v135, v137
	s_waitcnt lgkmcnt(2)
	v_fmac_f32_e32 v8, v138, v146
	v_fmac_f32_e32 v8, v139, v147
	s_waitcnt lgkmcnt(0)
	v_fmac_f32_e32 v8, v148, v150
	v_fmac_f32_e32 v8, v149, v151
	s_cbranch_scc1 .LBB0_610
	ds_read_b32 v9, v7 offset:49456
	s_mov_b32 s2, 0x3fb8aa3b
	v_mul_f32_e32 v8, v3, v8
	s_waitcnt lgkmcnt(0)
	v_sub_f32_e32 v9, v2, v9
	v_mul_f32_e32 v10, 0x3fb8aa3b, v9
	v_fma_f32 v11, v9, s2, -v10
	v_rndne_f32_e32 v12, v10
	v_fmac_f32_e32 v11, 0x32a5705f, v9
	v_sub_f32_e32 v10, v10, v12
	v_add_f32_e32 v10, v10, v11
	v_cvt_i32_f32_e32 v12, v12
	v_exp_f32_e32 v10, v10
	s_mov_b32 s2, 0xc2ce8ed0
	v_cmp_ngt_f32_e32 vcc, s2, v9
	s_mov_b32 s2, 0x42b17218
	v_ldexp_f32 v10, v10, v12
	v_cndmask_b32_e32 v10, 0, v10, vcc
	v_cmp_nlt_f32_e32 vcc, s2, v9
	s_nop 1
	v_cndmask_b32_e32 v9, v187, v10, vcc
	v_mul_f32_e32 v8, v8, v9

; DI void gdn_g1(const Params& p, int l, int ch, char* smem) {
;     ...
;   for (int i = 0; i < 16; ++i) { const int s = part + 4 * i; float a = 0.f;
;     if (s < c) { float dot = 0.f;
; #pragma unroll 16
;       for (int d = 0; d < 64; ++d) dot += sR[c * 129 + 64 + d] * sR[s * 129 + 64 + d];
;       a = bc * dot * expf(Gc - sG[s]); }
;     sA[c * 64 + s] = a; }
.LBB0_614:
	v_add_u32_e32 v14, s2, v5
	v_add_u32_e32 v15, s2, v9
	ds_read2_b32 v[114:115], v14 offset1:1
	ds_read2_b32 v[116:117], v15 offset1:1
	ds_read2_b32 v[118:119], v14 offset0:2 offset1:3
	ds_read2_b32 v[120:121], v15 offset0:2 offset1:3
	ds_read2_b32 v[122:123], v14 offset0:4 offset1:5
	ds_read2_b32 v[124:125], v15 offset0:4 offset1:5
	ds_read2_b32 v[126:127], v14 offset0:6 offset1:7
	ds_read2_b32 v[128:129], v15 offset0:6 offset1:7
	ds_read2_b32 v[130:131], v14 offset0:8 offset1:9
	ds_read2_b32 v[132:133], v15 offset0:8 offset1:9
	ds_read2_b32 v[134:135], v14 offset0:10 offset1:11
	ds_read2_b32 v[136:137], v15 offset0:10 offset1:11
	ds_read2_b32 v[138:139], v14 offset0:12 offset1:13
	ds_read2_b32 v[146:147], v15 offset0:12 offset1:13
	s_add_i32 s2, s2, 64
	s_cmpk_lg_i32 s2, 0x100
	s_waitcnt lgkmcnt(12)
	v_fmac_f32_e32 v8, v114, v116
	v_fmac_f32_e32 v8, v115, v117
	ds_read2_b32 v[148:149], v14 offset0:14 offset1:15
	ds_read2_b32 v[150:151], v15 offset0:14 offset1:15
	s_waitcnt lgkmcnt(12)
	v_fmac_f32_e32 v8, v118, v120
	v_fmac_f32_e32 v8, v119, v121
	s_waitcnt lgkmcnt(10)
	v_fmac_f32_e32 v8, v122, v124
	v_fmac_f32_e32 v8, v123, v125
	s_waitcnt lgkmcnt(8)
	v_fmac_f32_e32 v8, v126, v128
	v_fmac_f32_e32 v8, v127, v129
	s_waitcnt lgkmcnt(6)
	v_fmac_f32_e32 v8, v130, v132
	v_fmac_f32_e32 v8, v131, v133
	s_waitcnt lgkmcnt(4)
	v_fmac_f32_e32 v8, v134, v136
	v_fmac_f32_e32 v8, v135, v137
	s_waitcnt lgkmcnt(2)
	v_fmac_f32_e32 v8, v138, v146
	v_fmac_f32_e32 v8, v139, v147
	s_waitcnt lgkmcnt(0)
	v_fmac_f32_e32 v8, v148, v150
	v_fmac_f32_e32 v8, v149, v151
	s_cbranch_scc1 .LBB0_614
	ds_read_b32 v9, v7 offset:49472
	s_mov_b32 s2, 0x3fb8aa3b
	v_mul_f32_e32 v8, v3, v8
	s_waitcnt lgkmcnt(0)
	v_sub_f32_e32 v9, v2, v9
	v_mul_f32_e32 v10, 0x3fb8aa3b, v9
	v_fma_f32 v11, v9, s2, -v10
	v_rndne_f32_e32 v12, v10
	v_fmac_f32_e32 v11, 0x32a5705f, v9
	v_sub_f32_e32 v10, v10, v12
	v_add_f32_e32 v10, v10, v11
	v_cvt_i32_f32_e32 v12, v12
	v_exp_f32_e32 v10, v10
	s_mov_b32 s2, 0xc2ce8ed0
	v_cmp_ngt_f32_e32 vcc, s2, v9
	s_mov_b32 s2, 0x42b17218
	v_ldexp_f32 v10, v10, v12
	v_cndmask_b32_e32 v10, 0, v10, vcc
	v_cmp_nlt_f32_e32 vcc, s2, v9
	s_nop 1
	v_cndmask_b32_e32 v9, v187, v10, vcc
	v_mul_f32_e32 v8, v8, v9

; DI void gdn_g1(const Params& p, int l, int ch, char* smem) {
;     ...
;   for (int i = 0; i < 16; ++i) { const int s = part + 4 * i; float a = 0.f;
;     if (s < c) { float dot = 0.f;
; #pragma unroll 16
;       for (int d = 0; d < 64; ++d) dot += sR[c * 129 + 64 + d] * sR[s * 129 + 64 + d];
;       a = bc * dot * expf(Gc - sG[s]); }
;     sA[c * 64 + s] = a; }
.LBB0_618:
	v_add_u32_e32 v14, s2, v5
	v_add_u32_e32 v15, s2, v9
	ds_read2_b32 v[114:115], v14 offset1:1
	ds_read2_b32 v[116:117], v15 offset1:1
	ds_read2_b32 v[118:119], v14 offset0:2 offset1:3
	ds_read2_b32 v[120:121], v15 offset0:2 offset1:3
	ds_read2_b32 v[122:123], v14 offset0:4 offset1:5
	ds_read2_b32 v[124:125], v15 offset0:4 offset1:5
	ds_read2_b32 v[126:127], v14 offset0:6 offset1:7
	ds_read2_b32 v[128:129], v15 offset0:6 offset1:7
	ds_read2_b32 v[130:131], v14 offset0:8 offset1:9
	ds_read2_b32 v[132:133], v15 offset0:8 offset1:9
	ds_read2_b32 v[134:135], v14 offset0:10 offset1:11
	ds_read2_b32 v[136:137], v15 offset0:10 offset1:11
	ds_read2_b32 v[138:139], v14 offset0:12 offset1:13
	ds_read2_b32 v[146:147], v15 offset0:12 offset1:13
	s_add_i32 s2, s2, 64
	s_cmpk_lg_i32 s2, 0x100
	s_waitcnt lgkmcnt(12)
	v_fmac_f32_e32 v8, v114, v116
	v_fmac_f32_e32 v8, v115, v117
	ds_read2_b32 v[148:149], v14 offset0:14 offset1:15
	ds_read2_b32 v[150:151], v15 offset0:14 offset1:15
	s_waitcnt lgkmcnt(12)
	v_fmac_f32_e32 v8, v118, v120
	v_fmac_f32_e32 v8, v119, v121
	s_waitcnt lgkmcnt(10)
	v_fmac_f32_e32 v8, v122, v124
	v_fmac_f32_e32 v8, v123, v125
	s_waitcnt lgkmcnt(8)
	v_fmac_f32_e32 v8, v126, v128
	v_fmac_f32_e32 v8, v127, v129
	s_waitcnt lgkmcnt(6)
	v_fmac_f32_e32 v8, v130, v132
	v_fmac_f32_e32 v8, v131, v133
	s_waitcnt lgkmcnt(4)
	v_fmac_f32_e32 v8, v134, v136
	v_fmac_f32_e32 v8, v135, v137
	s_waitcnt lgkmcnt(2)
	v_fmac_f32_e32 v8, v138, v146
	v_fmac_f32_e32 v8, v139, v147
	s_waitcnt lgkmcnt(0)
	v_fmac_f32_e32 v8, v148, v150
	v_fmac_f32_e32 v8, v149, v151
	s_cbranch_scc1 .LBB0_618
	ds_read_b32 v9, v7 offset:49488
	s_mov_b32 s2, 0x3fb8aa3b
	v_mul_f32_e32 v8, v3, v8
	s_waitcnt lgkmcnt(0)
	v_sub_f32_e32 v9, v2, v9
	v_mul_f32_e32 v10, 0x3fb8aa3b, v9
	v_fma_f32 v11, v9, s2, -v10
	v_rndne_f32_e32 v12, v10
	v_fmac_f32_e32 v11, 0x32a5705f, v9
	v_sub_f32_e32 v10, v10, v12
	v_add_f32_e32 v10, v10, v11
	v_cvt_i32_f32_e32 v12, v12
	v_exp_f32_e32 v10, v10
	s_mov_b32 s2, 0xc2ce8ed0
	v_cmp_ngt_f32_e32 vcc, s2, v9
	s_mov_b32 s2, 0x42b17218
	v_ldexp_f32 v10, v10, v12
	v_cndmask_b32_e32 v10, 0, v10, vcc
	v_cmp_nlt_f32_e32 vcc, s2, v9
	s_nop 1
	v_cndmask_b32_e32 v9, v187, v10, vcc
	v_mul_f32_e32 v8, v8, v9

; DI void gdn_g1(const Params& p, int l, int ch, char* smem) {
;     ...
;   for (int i = 0; i < 16; ++i) { const int s = part + 4 * i; float a = 0.f;
;     if (s < c) { float dot = 0.f;
; #pragma unroll 16
;       for (int d = 0; d < 64; ++d) dot += sR[c * 129 + 64 + d] * sR[s * 129 + 64 + d];
;       a = bc * dot * expf(Gc - sG[s]); }
;     sA[c * 64 + s] = a; }
.LBB0_622:
	v_add_u32_e32 v14, s2, v5
	v_add_u32_e32 v15, s2, v9
	ds_read2_b32 v[114:115], v14 offset1:1
	ds_read2_b32 v[116:117], v15 offset1:1
	ds_read2_b32 v[118:119], v14 offset0:2 offset1:3
	ds_read2_b32 v[120:121], v15 offset0:2 offset1:3
	ds_read2_b32 v[122:123], v14 offset0:4 offset1:5
	ds_read2_b32 v[124:125], v15 offset0:4 offset1:5
	ds_read2_b32 v[126:127], v14 offset0:6 offset1:7
	ds_read2_b32 v[128:129], v15 offset0:6 offset1:7
	ds_read2_b32 v[130:131], v14 offset0:8 offset1:9
	ds_read2_b32 v[132:133], v15 offset0:8 offset1:9
	ds_read2_b32 v[134:135], v14 offset0:10 offset1:11
	ds_read2_b32 v[136:137], v15 offset0:10 offset1:11
	ds_read2_b32 v[138:139], v14 offset0:12 offset1:13
	ds_read2_b32 v[146:147], v15 offset0:12 offset1:13
	s_add_i32 s2, s2, 64
	s_cmpk_lg_i32 s2, 0x100
	s_waitcnt lgkmcnt(12)
	v_fmac_f32_e32 v8, v114, v116
	v_fmac_f32_e32 v8, v115, v117
	ds_read2_b32 v[148:149], v14 offset0:14 offset1:15
	ds_read2_b32 v[150:151], v15 offset0:14 offset1:15
	s_waitcnt lgkmcnt(12)
	v_fmac_f32_e32 v8, v118, v120
	v_fmac_f32_e32 v8, v119, v121
	s_waitcnt lgkmcnt(10)
	v_fmac_f32_e32 v8, v122, v124
	v_fmac_f32_e32 v8, v123, v125
	s_waitcnt lgkmcnt(8)
	v_fmac_f32_e32 v8, v126, v128
	v_fmac_f32_e32 v8, v127, v129
	s_waitcnt lgkmcnt(6)
	v_fmac_f32_e32 v8, v130, v132
	v_fmac_f32_e32 v8, v131, v133
	s_waitcnt lgkmcnt(4)
	v_fmac_f32_e32 v8, v134, v136
	v_fmac_f32_e32 v8, v135, v137
	s_waitcnt lgkmcnt(2)
	v_fmac_f32_e32 v8, v138, v146
	v_fmac_f32_e32 v8, v139, v147
	s_waitcnt lgkmcnt(0)
	v_fmac_f32_e32 v8, v148, v150
	v_fmac_f32_e32 v8, v149, v151
	s_cbranch_scc1 .LBB0_622
	ds_read_b32 v9, v7 offset:49504
	s_mov_b32 s2, 0x3fb8aa3b
	v_mul_f32_e32 v8, v3, v8
	s_waitcnt lgkmcnt(0)
	v_sub_f32_e32 v9, v2, v9
	v_mul_f32_e32 v10, 0x3fb8aa3b, v9
	v_fma_f32 v11, v9, s2, -v10
	v_rndne_f32_e32 v12, v10
	v_fmac_f32_e32 v11, 0x32a5705f, v9
	v_sub_f32_e32 v10, v10, v12
	v_add_f32_e32 v10, v10, v11
	v_cvt_i32_f32_e32 v12, v12
	v_exp_f32_e32 v10, v10
	s_mov_b32 s2, 0xc2ce8ed0
	v_cmp_ngt_f32_e32 vcc, s2, v9
	s_mov_b32 s2, 0x42b17218
	v_ldexp_f32 v10, v10, v12
	v_cndmask_b32_e32 v10, 0, v10, vcc
	v_cmp_nlt_f32_e32 vcc, s2, v9
	s_nop 1
	v_cndmask_b32_e32 v9, v187, v10, vcc
	v_mul_f32_e32 v8, v8, v9

; DI void gdn_g1(const Params& p, int l, int ch, char* smem) {
;     ...
;   for (int i = 0; i < 16; ++i) { const int s = part + 4 * i; float a = 0.f;
;     if (s < c) { float dot = 0.f;
; #pragma unroll 16
;       for (int d = 0; d < 64; ++d) dot += sR[c * 129 + 64 + d] * sR[s * 129 + 64 + d];
;       a = bc * dot * expf(Gc - sG[s]); }
;     sA[c * 64 + s] = a; }
.LBB0_626:
	v_add_u32_e32 v14, s2, v5
	v_add_u32_e32 v15, s2, v9
	ds_read2_b32 v[114:115], v14 offset1:1
	ds_read2_b32 v[116:117], v15 offset1:1
	ds_read2_b32 v[118:119], v14 offset0:2 offset1:3
	ds_read2_b32 v[120:121], v15 offset0:2 offset1:3
	ds_read2_b32 v[122:123], v14 offset0:4 offset1:5
	ds_read2_b32 v[124:125], v15 offset0:4 offset1:5
	ds_read2_b32 v[126:127], v14 offset0:6 offset1:7
	ds_read2_b32 v[128:129], v15 offset0:6 offset1:7
	ds_read2_b32 v[130:131], v14 offset0:8 offset1:9
	ds_read2_b32 v[132:133], v15 offset0:8 offset1:9
	ds_read2_b32 v[134:135], v14 offset0:10 offset1:11
	ds_read2_b32 v[136:137], v15 offset0:10 offset1:11
	ds_read2_b32 v[138:139], v14 offset0:12 offset1:13
	ds_read2_b32 v[146:147], v15 offset0:12 offset1:13
	s_add_i32 s2, s2, 64
	s_cmpk_lg_i32 s2, 0x100
	s_waitcnt lgkmcnt(12)
	v_fmac_f32_e32 v8, v114, v116
	v_fmac_f32_e32 v8, v115, v117
	ds_read2_b32 v[148:149], v14 offset0:14 offset1:15
	ds_read2_b32 v[150:151], v15 offset0:14 offset1:15
	s_waitcnt lgkmcnt(12)
	v_fmac_f32_e32 v8, v118, v120
	v_fmac_f32_e32 v8, v119, v121
	s_waitcnt lgkmcnt(10)
	v_fmac_f32_e32 v8, v122, v124
	v_fmac_f32_e32 v8, v123, v125
	s_waitcnt lgkmcnt(8)
	v_fmac_f32_e32 v8, v126, v128
	v_fmac_f32_e32 v8, v127, v129
	s_waitcnt lgkmcnt(6)
	v_fmac_f32_e32 v8, v130, v132
	v_fmac_f32_e32 v8, v131, v133
	s_waitcnt lgkmcnt(4)
	v_fmac_f32_e32 v8, v134, v136
	v_fmac_f32_e32 v8, v135, v137
	s_waitcnt lgkmcnt(2)
	v_fmac_f32_e32 v8, v138, v146
	v_fmac_f32_e32 v8, v139, v147
	s_waitcnt lgkmcnt(0)
	v_fmac_f32_e32 v8, v148, v150
	v_fmac_f32_e32 v8, v149, v151
	s_cbranch_scc1 .LBB0_626
	ds_read_b32 v9, v7 offset:49520
	s_mov_b32 s2, 0x3fb8aa3b
	v_mul_f32_e32 v8, v3, v8
	s_waitcnt lgkmcnt(0)
	v_sub_f32_e32 v9, v2, v9
	v_mul_f32_e32 v10, 0x3fb8aa3b, v9
	v_fma_f32 v11, v9, s2, -v10
	v_rndne_f32_e32 v12, v10
	v_fmac_f32_e32 v11, 0x32a5705f, v9
	v_sub_f32_e32 v10, v10, v12
	v_add_f32_e32 v10, v10, v11
	v_cvt_i32_f32_e32 v12, v12
	v_exp_f32_e32 v10, v10
	s_mov_b32 s2, 0xc2ce8ed0
	v_cmp_ngt_f32_e32 vcc, s2, v9
	s_mov_b32 s2, 0x42b17218
	v_ldexp_f32 v10, v10, v12
	v_cndmask_b32_e32 v10, 0, v10, vcc
	v_cmp_nlt_f32_e32 vcc, s2, v9
	s_nop 1
	v_cndmask_b32_e32 v9, v187, v10, vcc
	v_mul_f32_e32 v8, v8, v9

; DI void gdn_g1(const Params& p, int l, int ch, char* smem) {
;     ...
;   for (int i = 0; i < 16; ++i) { const int s = part + 4 * i; float a = 0.f;
;     if (s < c) { float dot = 0.f;
; #pragma unroll 16
;       for (int d = 0; d < 64; ++d) dot += sR[c * 129 + 64 + d] * sR[s * 129 + 64 + d];
;       a = bc * dot * expf(Gc - sG[s]); }
;     sA[c * 64 + s] = a; }
.LBB0_630:
	v_add_u32_e32 v14, s2, v5
	v_add_u32_e32 v15, s2, v9
	ds_read2_b32 v[114:115], v14 offset1:1
	ds_read2_b32 v[116:117], v15 offset1:1
	ds_read2_b32 v[118:119], v14 offset0:2 offset1:3
	ds_read2_b32 v[120:121], v15 offset0:2 offset1:3
	ds_read2_b32 v[122:123], v14 offset0:4 offset1:5
	ds_read2_b32 v[124:125], v15 offset0:4 offset1:5
	ds_read2_b32 v[126:127], v14 offset0:6 offset1:7
	ds_read2_b32 v[128:129], v15 offset0:6 offset1:7
	ds_read2_b32 v[130:131], v14 offset0:8 offset1:9
	ds_read2_b32 v[132:133], v15 offset0:8 offset1:9
	ds_read2_b32 v[134:135], v14 offset0:10 offset1:11
	ds_read2_b32 v[136:137], v15 offset0:10 offset1:11
	ds_read2_b32 v[138:139], v14 offset0:12 offset1:13
	ds_read2_b32 v[146:147], v15 offset0:12 offset1:13
	s_add_i32 s2, s2, 64
	s_cmpk_lg_i32 s2, 0x100
	s_waitcnt lgkmcnt(12)
	v_fmac_f32_e32 v8, v114, v116
	v_fmac_f32_e32 v8, v115, v117
	ds_read2_b32 v[148:149], v14 offset0:14 offset1:15
	ds_read2_b32 v[150:151], v15 offset0:14 offset1:15
	s_waitcnt lgkmcnt(12)
	v_fmac_f32_e32 v8, v118, v120
	v_fmac_f32_e32 v8, v119, v121
	s_waitcnt lgkmcnt(10)
	v_fmac_f32_e32 v8, v122, v124
	v_fmac_f32_e32 v8, v123, v125
	s_waitcnt lgkmcnt(8)
	v_fmac_f32_e32 v8, v126, v128
	v_fmac_f32_e32 v8, v127, v129
	s_waitcnt lgkmcnt(6)
	v_fmac_f32_e32 v8, v130, v132
	v_fmac_f32_e32 v8, v131, v133
	s_waitcnt lgkmcnt(4)
	v_fmac_f32_e32 v8, v134, v136
	v_fmac_f32_e32 v8, v135, v137
	s_waitcnt lgkmcnt(2)
	v_fmac_f32_e32 v8, v138, v146
	v_fmac_f32_e32 v8, v139, v147
	s_waitcnt lgkmcnt(0)
	v_fmac_f32_e32 v8, v148, v150
	v_fmac_f32_e32 v8, v149, v151
	s_cbranch_scc1 .LBB0_630
	ds_read_b32 v9, v7 offset:49536
	s_mov_b32 s2, 0x3fb8aa3b
	v_mul_f32_e32 v8, v3, v8
	s_waitcnt lgkmcnt(0)
	v_sub_f32_e32 v9, v2, v9
	v_mul_f32_e32 v10, 0x3fb8aa3b, v9
	v_fma_f32 v11, v9, s2, -v10
	v_rndne_f32_e32 v12, v10
	v_fmac_f32_e32 v11, 0x32a5705f, v9
	v_sub_f32_e32 v10, v10, v12
	v_add_f32_e32 v10, v10, v11
	v_cvt_i32_f32_e32 v12, v12
	v_exp_f32_e32 v10, v10
	s_mov_b32 s2, 0xc2ce8ed0
	v_cmp_ngt_f32_e32 vcc, s2, v9
	s_mov_b32 s2, 0x42b17218
	v_ldexp_f32 v10, v10, v12
	v_cndmask_b32_e32 v10, 0, v10, vcc
	v_cmp_nlt_f32_e32 vcc, s2, v9
	s_nop 1
	v_cndmask_b32_e32 v9, v187, v10, vcc
	v_mul_f32_e32 v8, v8, v9

; DI void gdn_g1(const Params& p, int l, int ch, char* smem) {
;     ...
;   for (int i = 0; i < 16; ++i) { const int s = part + 4 * i; float a = 0.f;
;     if (s < c) { float dot = 0.f;
; #pragma unroll 16
;       for (int d = 0; d < 64; ++d) dot += sR[c * 129 + 64 + d] * sR[s * 129 + 64 + d];
;       a = bc * dot * expf(Gc - sG[s]); }
;     sA[c * 64 + s] = a; }
.LBB0_634:
	v_add_u32_e32 v14, s2, v5
	v_add_u32_e32 v15, s2, v9
	ds_read2_b32 v[114:115], v14 offset1:1
	ds_read2_b32 v[116:117], v15 offset1:1
	ds_read2_b32 v[118:119], v14 offset0:2 offset1:3
	ds_read2_b32 v[120:121], v15 offset0:2 offset1:3
	ds_read2_b32 v[122:123], v14 offset0:4 offset1:5
	ds_read2_b32 v[124:125], v15 offset0:4 offset1:5
	ds_read2_b32 v[126:127], v14 offset0:6 offset1:7
	ds_read2_b32 v[128:129], v15 offset0:6 offset1:7
	ds_read2_b32 v[130:131], v14 offset0:8 offset1:9
	ds_read2_b32 v[132:133], v15 offset0:8 offset1:9
	ds_read2_b32 v[134:135], v14 offset0:10 offset1:11
	ds_read2_b32 v[136:137], v15 offset0:10 offset1:11
	ds_read2_b32 v[138:139], v14 offset0:12 offset1:13
	ds_read2_b32 v[146:147], v15 offset0:12 offset1:13
	s_add_i32 s2, s2, 64
	s_cmpk_lg_i32 s2, 0x100
	s_waitcnt lgkmcnt(12)
	v_fmac_f32_e32 v8, v114, v116
	v_fmac_f32_e32 v8, v115, v117
	ds_read2_b32 v[148:149], v14 offset0:14 offset1:15
	ds_read2_b32 v[150:151], v15 offset0:14 offset1:15
	s_waitcnt lgkmcnt(12)
	v_fmac_f32_e32 v8, v118, v120
	v_fmac_f32_e32 v8, v119, v121
	s_waitcnt lgkmcnt(10)
	v_fmac_f32_e32 v8, v122, v124
	v_fmac_f32_e32 v8, v123, v125
	s_waitcnt lgkmcnt(8)
	v_fmac_f32_e32 v8, v126, v128
	v_fmac_f32_e32 v8, v127, v129
	s_waitcnt lgkmcnt(6)
	v_fmac_f32_e32 v8, v130, v132
	v_fmac_f32_e32 v8, v131, v133
	s_waitcnt lgkmcnt(4)
	v_fmac_f32_e32 v8, v134, v136
	v_fmac_f32_e32 v8, v135, v137
	s_waitcnt lgkmcnt(2)
	v_fmac_f32_e32 v8, v138, v146
	v_fmac_f32_e32 v8, v139, v147
	s_waitcnt lgkmcnt(0)
	v_fmac_f32_e32 v8, v148, v150
	v_fmac_f32_e32 v8, v149, v151
	s_cbranch_scc1 .LBB0_634
	ds_read_b32 v9, v7 offset:49552
	s_mov_b32 s2, 0x3fb8aa3b
	v_mul_f32_e32 v8, v3, v8
	s_waitcnt lgkmcnt(0)
	v_sub_f32_e32 v9, v2, v9
	v_mul_f32_e32 v10, 0x3fb8aa3b, v9
	v_fma_f32 v11, v9, s2, -v10
	v_rndne_f32_e32 v12, v10
	v_fmac_f32_e32 v11, 0x32a5705f, v9
	v_sub_f32_e32 v10, v10, v12
	v_add_f32_e32 v10, v10, v11
	v_cvt_i32_f32_e32 v12, v12
	v_exp_f32_e32 v10, v10
	s_mov_b32 s2, 0xc2ce8ed0
	v_cmp_ngt_f32_e32 vcc, s2, v9
	s_mov_b32 s2, 0x42b17218
	v_ldexp_f32 v10, v10, v12
	v_cndmask_b32_e32 v10, 0, v10, vcc
	v_cmp_nlt_f32_e32 vcc, s2, v9
	s_nop 1
	v_cndmask_b32_e32 v9, v187, v10, vcc
	v_mul_f32_e32 v8, v8, v9

; DI void gdn_g1(const Params& p, int l, int ch, char* smem) {
;     ...
;   for (int i = 0; i < 16; ++i) { const int s = part + 4 * i; float a = 0.f;
;     if (s < c) { float dot = 0.f;
; #pragma unroll 16
;       for (int d = 0; d < 64; ++d) dot += sR[c * 129 + 64 + d] * sR[s * 129 + 64 + d];
;       a = bc * dot * expf(Gc - sG[s]); }
;     sA[c * 64 + s] = a; }
.LBB0_638:
	v_add_u32_e32 v14, s2, v5
	v_add_u32_e32 v15, s2, v9
	ds_read2_b32 v[114:115], v14 offset1:1
	ds_read2_b32 v[116:117], v15 offset1:1
	ds_read2_b32 v[118:119], v14 offset0:2 offset1:3
	ds_read2_b32 v[120:121], v15 offset0:2 offset1:3
	ds_read2_b32 v[122:123], v14 offset0:4 offset1:5
	ds_read2_b32 v[124:125], v15 offset0:4 offset1:5
	ds_read2_b32 v[126:127], v14 offset0:6 offset1:7
	ds_read2_b32 v[128:129], v15 offset0:6 offset1:7
	ds_read2_b32 v[130:131], v14 offset0:8 offset1:9
	ds_read2_b32 v[132:133], v15 offset0:8 offset1:9
	ds_read2_b32 v[134:135], v14 offset0:10 offset1:11
	ds_read2_b32 v[136:137], v15 offset0:10 offset1:11
	ds_read2_b32 v[138:139], v14 offset0:12 offset1:13
	ds_read2_b32 v[146:147], v15 offset0:12 offset1:13
	s_add_i32 s2, s2, 64
	s_cmpk_lg_i32 s2, 0x100
	s_waitcnt lgkmcnt(12)
	v_fmac_f32_e32 v8, v114, v116
	v_fmac_f32_e32 v8, v115, v117
	ds_read2_b32 v[148:149], v14 offset0:14 offset1:15
	ds_read2_b32 v[150:151], v15 offset0:14 offset1:15
	s_waitcnt lgkmcnt(12)
	v_fmac_f32_e32 v8, v118, v120
	v_fmac_f32_e32 v8, v119, v121
	s_waitcnt lgkmcnt(10)
	v_fmac_f32_e32 v8, v122, v124
	v_fmac_f32_e32 v8, v123, v125
	s_waitcnt lgkmcnt(8)
	v_fmac_f32_e32 v8, v126, v128
	v_fmac_f32_e32 v8, v127, v129
	s_waitcnt lgkmcnt(6)
	v_fmac_f32_e32 v8, v130, v132
	v_fmac_f32_e32 v8, v131, v133
	s_waitcnt lgkmcnt(4)
	v_fmac_f32_e32 v8, v134, v136
	v_fmac_f32_e32 v8, v135, v137
	s_waitcnt lgkmcnt(2)
	v_fmac_f32_e32 v8, v138, v146
	v_fmac_f32_e32 v8, v139, v147
	s_waitcnt lgkmcnt(0)
	v_fmac_f32_e32 v8, v148, v150
	v_fmac_f32_e32 v8, v149, v151
	s_cbranch_scc1 .LBB0_638
	ds_read_b32 v9, v7 offset:49568
	s_mov_b32 s2, 0x3fb8aa3b
	v_mul_f32_e32 v8, v3, v8
	s_waitcnt lgkmcnt(0)
	v_sub_f32_e32 v9, v2, v9
	v_mul_f32_e32 v10, 0x3fb8aa3b, v9
	v_fma_f32 v11, v9, s2, -v10
	v_rndne_f32_e32 v12, v10
	v_fmac_f32_e32 v11, 0x32a5705f, v9
	v_sub_f32_e32 v10, v10, v12
	v_add_f32_e32 v10, v10, v11
	v_cvt_i32_f32_e32 v12, v12
	v_exp_f32_e32 v10, v10
	s_mov_b32 s2, 0xc2ce8ed0
	v_cmp_ngt_f32_e32 vcc, s2, v9
	s_mov_b32 s2, 0x42b17218
	v_ldexp_f32 v10, v10, v12
	v_cndmask_b32_e32 v10, 0, v10, vcc
	v_cmp_nlt_f32_e32 vcc, s2, v9
	s_nop 1
	v_cndmask_b32_e32 v9, v187, v10, vcc
	v_mul_f32_e32 v8, v8, v9

; DI void gdn_g1(const Params& p, int l, int ch, char* smem) {
;     ...
;   for (int i = 0; i < 16; ++i) { const int s = part + 4 * i; float a = 0.f;
;     if (s < c) { float dot = 0.f;
; #pragma unroll 16
;       for (int d = 0; d < 64; ++d) dot += sR[c * 129 + 64 + d] * sR[s * 129 + 64 + d];
;       a = bc * dot * expf(Gc - sG[s]); }
;     sA[c * 64 + s] = a; }
.LBB0_642:
	v_add_u32_e32 v14, s2, v5
	v_add_u32_e32 v15, s2, v9
	ds_read2_b32 v[114:115], v14 offset1:1
	ds_read2_b32 v[116:117], v15 offset1:1
	ds_read2_b32 v[118:119], v14 offset0:2 offset1:3
	ds_read2_b32 v[120:121], v15 offset0:2 offset1:3
	ds_read2_b32 v[122:123], v14 offset0:4 offset1:5
	ds_read2_b32 v[124:125], v15 offset0:4 offset1:5
	ds_read2_b32 v[126:127], v14 offset0:6 offset1:7
	ds_read2_b32 v[128:129], v15 offset0:6 offset1:7
	ds_read2_b32 v[130:131], v14 offset0:8 offset1:9
	ds_read2_b32 v[132:133], v15 offset0:8 offset1:9
	ds_read2_b32 v[134:135], v14 offset0:10 offset1:11
	ds_read2_b32 v[136:137], v15 offset0:10 offset1:11
	ds_read2_b32 v[138:139], v14 offset0:12 offset1:13
	ds_read2_b32 v[146:147], v15 offset0:12 offset1:13
	s_add_i32 s2, s2, 64
	s_cmpk_lg_i32 s2, 0x100
	s_waitcnt lgkmcnt(12)
	v_fmac_f32_e32 v8, v114, v116
	v_fmac_f32_e32 v8, v115, v117
	ds_read2_b32 v[148:149], v14 offset0:14 offset1:15
	ds_read2_b32 v[150:151], v15 offset0:14 offset1:15
	s_waitcnt lgkmcnt(12)
	v_fmac_f32_e32 v8, v118, v120
	v_fmac_f32_e32 v8, v119, v121
	s_waitcnt lgkmcnt(10)
	v_fmac_f32_e32 v8, v122, v124
	v_fmac_f32_e32 v8, v123, v125
	s_waitcnt lgkmcnt(8)
	v_fmac_f32_e32 v8, v126, v128
	v_fmac_f32_e32 v8, v127, v129
	s_waitcnt lgkmcnt(6)
	v_fmac_f32_e32 v8, v130, v132
	v_fmac_f32_e32 v8, v131, v133
	s_waitcnt lgkmcnt(4)
	v_fmac_f32_e32 v8, v134, v136
	v_fmac_f32_e32 v8, v135, v137
	s_waitcnt lgkmcnt(2)
	v_fmac_f32_e32 v8, v138, v146
	v_fmac_f32_e32 v8, v139, v147
	s_waitcnt lgkmcnt(0)
	v_fmac_f32_e32 v8, v148, v150
	v_fmac_f32_e32 v8, v149, v151
	s_cbranch_scc1 .LBB0_642
	ds_read_b32 v9, v7 offset:49584
	s_mov_b32 s2, 0x3fb8aa3b
	v_mul_f32_e32 v8, v3, v8
	s_waitcnt lgkmcnt(0)
	v_sub_f32_e32 v9, v2, v9
	v_mul_f32_e32 v10, 0x3fb8aa3b, v9
	v_fma_f32 v11, v9, s2, -v10
	v_rndne_f32_e32 v12, v10
	v_fmac_f32_e32 v11, 0x32a5705f, v9
	v_sub_f32_e32 v10, v10, v12
	v_add_f32_e32 v10, v10, v11
	v_cvt_i32_f32_e32 v12, v12
	v_exp_f32_e32 v10, v10
	s_mov_b32 s2, 0xc2ce8ed0
	v_cmp_ngt_f32_e32 vcc, s2, v9
	s_mov_b32 s2, 0x42b17218
	v_ldexp_f32 v10, v10, v12
	v_cndmask_b32_e32 v10, 0, v10, vcc
	v_cmp_nlt_f32_e32 vcc, s2, v9
	s_nop 1
	v_cndmask_b32_e32 v9, v187, v10, vcc
	v_mul_f32_e32 v8, v8, v9

; DI void gdn_g1(const Params& p, int l, int ch, char* smem) {
;     ...
;   for (int i = 0; i < 16; ++i) { const int s = part + 4 * i; float a = 0.f;
;     if (s < c) { float dot = 0.f;
; #pragma unroll 16
;       for (int d = 0; d < 64; ++d) dot += sR[c * 129 + 64 + d] * sR[s * 129 + 64 + d];
;       a = bc * dot * expf(Gc - sG[s]); }
;     sA[c * 64 + s] = a; }
.LBB0_646:
	v_add_u32_e32 v14, s2, v5
	v_add_u32_e32 v15, s2, v9
	ds_read2_b32 v[114:115], v14 offset1:1
	ds_read2_b32 v[116:117], v15 offset1:1
	ds_read2_b32 v[118:119], v14 offset0:2 offset1:3
	ds_read2_b32 v[120:121], v15 offset0:2 offset1:3
	ds_read2_b32 v[122:123], v14 offset0:4 offset1:5
	ds_read2_b32 v[124:125], v15 offset0:4 offset1:5
	ds_read2_b32 v[126:127], v14 offset0:6 offset1:7
	ds_read2_b32 v[128:129], v15 offset0:6 offset1:7
	ds_read2_b32 v[130:131], v14 offset0:8 offset1:9
	ds_read2_b32 v[132:133], v15 offset0:8 offset1:9
	ds_read2_b32 v[134:135], v14 offset0:10 offset1:11
	ds_read2_b32 v[136:137], v15 offset0:10 offset1:11
	ds_read2_b32 v[138:139], v14 offset0:12 offset1:13
	ds_read2_b32 v[146:147], v15 offset0:12 offset1:13
	s_add_i32 s2, s2, 64
	s_cmpk_lg_i32 s2, 0x100
	s_waitcnt lgkmcnt(12)
	v_fmac_f32_e32 v8, v114, v116
	v_fmac_f32_e32 v8, v115, v117
	ds_read2_b32 v[148:149], v14 offset0:14 offset1:15
	ds_read2_b32 v[150:151], v15 offset0:14 offset1:15
	s_waitcnt lgkmcnt(12)
	v_fmac_f32_e32 v8, v118, v120
	v_fmac_f32_e32 v8, v119, v121
	s_waitcnt lgkmcnt(10)
	v_fmac_f32_e32 v8, v122, v124
	v_fmac_f32_e32 v8, v123, v125
	s_waitcnt lgkmcnt(8)
	v_fmac_f32_e32 v8, v126, v128
	v_fmac_f32_e32 v8, v127, v129
	s_waitcnt lgkmcnt(6)
	v_fmac_f32_e32 v8, v130, v132
	v_fmac_f32_e32 v8, v131, v133
	s_waitcnt lgkmcnt(4)
	v_fmac_f32_e32 v8, v134, v136
	v_fmac_f32_e32 v8, v135, v137
	s_waitcnt lgkmcnt(2)
	v_fmac_f32_e32 v8, v138, v146
	v_fmac_f32_e32 v8, v139, v147
	s_waitcnt lgkmcnt(0)
	v_fmac_f32_e32 v8, v148, v150
	v_fmac_f32_e32 v8, v149, v151
	s_cbranch_scc1 .LBB0_646
	ds_read_b32 v9, v7 offset:49600
	s_mov_b32 s2, 0x3fb8aa3b
	v_mul_f32_e32 v8, v3, v8
	s_waitcnt lgkmcnt(0)
	v_sub_f32_e32 v9, v2, v9
	v_mul_f32_e32 v10, 0x3fb8aa3b, v9
	v_fma_f32 v11, v9, s2, -v10
	v_rndne_f32_e32 v12, v10
	v_fmac_f32_e32 v11, 0x32a5705f, v9
	v_sub_f32_e32 v10, v10, v12
	v_add_f32_e32 v10, v10, v11
	v_cvt_i32_f32_e32 v12, v12
	v_exp_f32_e32 v10, v10
	s_mov_b32 s2, 0xc2ce8ed0
	v_cmp_ngt_f32_e32 vcc, s2, v9
	s_mov_b32 s2, 0x42b17218
	v_ldexp_f32 v10, v10, v12
	v_cndmask_b32_e32 v10, 0, v10, vcc
	v_cmp_nlt_f32_e32 vcc, s2, v9
	s_nop 1
	v_cndmask_b32_e32 v9, v187, v10, vcc
	v_mul_f32_e32 v8, v8, v9

; DI void gdn_g1(const Params& p, int l, int ch, char* smem) {
;     ...
;   for (int i = 0; i < 16; ++i) { const int s = part + 4 * i; float a = 0.f;
;     if (s < c) { float dot = 0.f;
; #pragma unroll 16
;       for (int d = 0; d < 64; ++d) dot += sR[c * 129 + 64 + d] * sR[s * 129 + 64 + d];
;       a = bc * dot * expf(Gc - sG[s]); }
;     sA[c * 64 + s] = a; }
.LBB0_650:
	v_add_u32_e32 v14, s2, v5
	v_add_u32_e32 v15, s2, v9
	ds_read2_b32 v[114:115], v14 offset1:1
	ds_read2_b32 v[116:117], v15 offset1:1
	ds_read2_b32 v[118:119], v14 offset0:2 offset1:3
	ds_read2_b32 v[120:121], v15 offset0:2 offset1:3
	ds_read2_b32 v[122:123], v14 offset0:4 offset1:5
	ds_read2_b32 v[124:125], v15 offset0:4 offset1:5
	ds_read2_b32 v[126:127], v14 offset0:6 offset1:7
	ds_read2_b32 v[128:129], v15 offset0:6 offset1:7
	ds_read2_b32 v[130:131], v14 offset0:8 offset1:9
	ds_read2_b32 v[132:133], v15 offset0:8 offset1:9
	ds_read2_b32 v[134:135], v14 offset0:10 offset1:11
	ds_read2_b32 v[136:137], v15 offset0:10 offset1:11
	ds_read2_b32 v[138:139], v14 offset0:12 offset1:13
	ds_read2_b32 v[146:147], v15 offset0:12 offset1:13
	s_add_i32 s2, s2, 64
	s_cmpk_lg_i32 s2, 0x100
	s_waitcnt lgkmcnt(12)
	v_fmac_f32_e32 v8, v114, v116
	v_fmac_f32_e32 v8, v115, v117
	ds_read2_b32 v[148:149], v14 offset0:14 offset1:15
	ds_read2_b32 v[150:151], v15 offset0:14 offset1:15
	s_waitcnt lgkmcnt(12)
	v_fmac_f32_e32 v8, v118, v120
	v_fmac_f32_e32 v8, v119, v121
	s_waitcnt lgkmcnt(10)
	v_fmac_f32_e32 v8, v122, v124
	v_fmac_f32_e32 v8, v123, v125
	s_waitcnt lgkmcnt(8)
	v_fmac_f32_e32 v8, v126, v128
	v_fmac_f32_e32 v8, v127, v129
	s_waitcnt lgkmcnt(6)
	v_fmac_f32_e32 v8, v130, v132
	v_fmac_f32_e32 v8, v131, v133
	s_waitcnt lgkmcnt(4)
	v_fmac_f32_e32 v8, v134, v136
	v_fmac_f32_e32 v8, v135, v137
	s_waitcnt lgkmcnt(2)
	v_fmac_f32_e32 v8, v138, v146
	v_fmac_f32_e32 v8, v139, v147
	s_waitcnt lgkmcnt(0)
	v_fmac_f32_e32 v8, v148, v150
	v_fmac_f32_e32 v8, v149, v151
	s_cbranch_scc1 .LBB0_650
	ds_read_b32 v9, v7 offset:49616
	s_mov_b32 s2, 0x3fb8aa3b
	v_mul_f32_e32 v8, v3, v8
	s_waitcnt lgkmcnt(0)
	v_sub_f32_e32 v9, v2, v9
	v_mul_f32_e32 v10, 0x3fb8aa3b, v9
	v_fma_f32 v11, v9, s2, -v10
	v_rndne_f32_e32 v12, v10
	v_fmac_f32_e32 v11, 0x32a5705f, v9
	v_sub_f32_e32 v10, v10, v12
	v_add_f32_e32 v10, v10, v11
	v_cvt_i32_f32_e32 v12, v12
	v_exp_f32_e32 v10, v10
	s_mov_b32 s2, 0xc2ce8ed0
	v_cmp_ngt_f32_e32 vcc, s2, v9
	s_mov_b32 s2, 0x42b17218
	v_ldexp_f32 v10, v10, v12
	v_cndmask_b32_e32 v10, 0, v10, vcc
	v_cmp_nlt_f32_e32 vcc, s2, v9
	s_nop 1
	v_cndmask_b32_e32 v9, v187, v10, vcc
	v_mul_f32_e32 v8, v8, v9

; DI void gdn_g1(const Params& p, int l, int ch, char* smem) {
;     ...
;   for (int i = 0; i < 16; ++i) { const int s = part + 4 * i; float a = 0.f;
;     if (s < c) { float dot = 0.f;
; #pragma unroll 16
;       for (int d = 0; d < 64; ++d) dot += sR[c * 129 + 64 + d] * sR[s * 129 + 64 + d];
;       a = bc * dot * expf(Gc - sG[s]); }
;     sA[c * 64 + s] = a; }
.LBB0_654:
	v_add_u32_e32 v14, s2, v5
	v_add_u32_e32 v15, s2, v9
	ds_read2_b32 v[114:115], v14 offset1:1
	ds_read2_b32 v[116:117], v15 offset1:1
	ds_read2_b32 v[118:119], v14 offset0:2 offset1:3
	ds_read2_b32 v[120:121], v15 offset0:2 offset1:3
	ds_read2_b32 v[122:123], v14 offset0:4 offset1:5
	ds_read2_b32 v[124:125], v15 offset0:4 offset1:5
	ds_read2_b32 v[126:127], v14 offset0:6 offset1:7
	ds_read2_b32 v[128:129], v15 offset0:6 offset1:7
	ds_read2_b32 v[130:131], v14 offset0:8 offset1:9
	ds_read2_b32 v[132:133], v15 offset0:8 offset1:9
	ds_read2_b32 v[134:135], v14 offset0:10 offset1:11
	ds_read2_b32 v[136:137], v15 offset0:10 offset1:11
	ds_read2_b32 v[138:139], v14 offset0:12 offset1:13
	ds_read2_b32 v[146:147], v15 offset0:12 offset1:13
	s_add_i32 s2, s2, 64
	s_cmpk_lg_i32 s2, 0x100
	s_waitcnt lgkmcnt(12)
	v_fmac_f32_e32 v8, v114, v116
	v_fmac_f32_e32 v8, v115, v117
	ds_read2_b32 v[148:149], v14 offset0:14 offset1:15
	ds_read2_b32 v[150:151], v15 offset0:14 offset1:15
	s_waitcnt lgkmcnt(12)
	v_fmac_f32_e32 v8, v118, v120
	v_fmac_f32_e32 v8, v119, v121
	s_waitcnt lgkmcnt(10)
	v_fmac_f32_e32 v8, v122, v124
	v_fmac_f32_e32 v8, v123, v125
	s_waitcnt lgkmcnt(8)
	v_fmac_f32_e32 v8, v126, v128
	v_fmac_f32_e32 v8, v127, v129
	s_waitcnt lgkmcnt(6)
	v_fmac_f32_e32 v8, v130, v132
	v_fmac_f32_e32 v8, v131, v133
	s_waitcnt lgkmcnt(4)
	v_fmac_f32_e32 v8, v134, v136
	v_fmac_f32_e32 v8, v135, v137
	s_waitcnt lgkmcnt(2)
	v_fmac_f32_e32 v8, v138, v146
	v_fmac_f32_e32 v8, v139, v147
	s_waitcnt lgkmcnt(0)
	v_fmac_f32_e32 v8, v148, v150
	v_fmac_f32_e32 v8, v149, v151
	s_cbranch_scc1 .LBB0_654
	ds_read_b32 v9, v7 offset:49632
	s_mov_b32 s2, 0x3fb8aa3b
	v_mul_f32_e32 v8, v3, v8
	s_waitcnt lgkmcnt(0)
	v_sub_f32_e32 v9, v2, v9
	v_mul_f32_e32 v10, 0x3fb8aa3b, v9
	v_fma_f32 v11, v9, s2, -v10
	v_rndne_f32_e32 v12, v10
	v_fmac_f32_e32 v11, 0x32a5705f, v9
	v_sub_f32_e32 v10, v10, v12
	v_add_f32_e32 v10, v10, v11
	v_cvt_i32_f32_e32 v12, v12
	v_exp_f32_e32 v10, v10
	s_mov_b32 s2, 0xc2ce8ed0
	v_cmp_ngt_f32_e32 vcc, s2, v9
	s_mov_b32 s2, 0x42b17218
	v_ldexp_f32 v10, v10, v12
	v_cndmask_b32_e32 v10, 0, v10, vcc
	v_cmp_nlt_f32_e32 vcc, s2, v9
	s_nop 1
	v_cndmask_b32_e32 v9, v187, v10, vcc
	v_mul_f32_e32 v8, v8, v9

; DI void gdn_g1(const Params& p, int l, int ch, char* smem) {
;     ...
;   for (int i = 0; i < 16; ++i) { const int s = part + 4 * i; float a = 0.f;
;     if (s < c) { float dot = 0.f;
; #pragma unroll 16
;       for (int d = 0; d < 64; ++d) dot += sR[c * 129 + 64 + d] * sR[s * 129 + 64 + d];
;       a = bc * dot * expf(Gc - sG[s]); }
;     sA[c * 64 + s] = a; }
.LBB0_658:
	v_add_u32_e32 v14, s2, v5
	v_add_u32_e32 v15, s2, v9
	ds_read2_b32 v[114:115], v14 offset1:1
	ds_read2_b32 v[116:117], v15 offset1:1
	ds_read2_b32 v[118:119], v14 offset0:2 offset1:3
	ds_read2_b32 v[120:121], v15 offset0:2 offset1:3
	ds_read2_b32 v[122:123], v14 offset0:4 offset1:5
	ds_read2_b32 v[124:125], v15 offset0:4 offset1:5
	ds_read2_b32 v[126:127], v14 offset0:6 offset1:7
	ds_read2_b32 v[128:129], v15 offset0:6 offset1:7
	ds_read2_b32 v[130:131], v14 offset0:8 offset1:9
	ds_read2_b32 v[132:133], v15 offset0:8 offset1:9
	ds_read2_b32 v[134:135], v14 offset0:10 offset1:11
	ds_read2_b32 v[136:137], v15 offset0:10 offset1:11
	ds_read2_b32 v[138:139], v14 offset0:12 offset1:13
	ds_read2_b32 v[146:147], v15 offset0:12 offset1:13
	s_add_i32 s2, s2, 64
	s_cmpk_lg_i32 s2, 0x100
	s_waitcnt lgkmcnt(12)
	v_fmac_f32_e32 v8, v114, v116
	v_fmac_f32_e32 v8, v115, v117
	ds_read2_b32 v[148:149], v14 offset0:14 offset1:15
	ds_read2_b32 v[150:151], v15 offset0:14 offset1:15
	s_waitcnt lgkmcnt(12)
	v_fmac_f32_e32 v8, v118, v120
	v_fmac_f32_e32 v8, v119, v121
	s_waitcnt lgkmcnt(10)
	v_fmac_f32_e32 v8, v122, v124
	v_fmac_f32_e32 v8, v123, v125
	s_waitcnt lgkmcnt(8)
	v_fmac_f32_e32 v8, v126, v128
	v_fmac_f32_e32 v8, v127, v129
	s_waitcnt lgkmcnt(6)
	v_fmac_f32_e32 v8, v130, v132
	v_fmac_f32_e32 v8, v131, v133
	s_waitcnt lgkmcnt(4)
	v_fmac_f32_e32 v8, v134, v136
	v_fmac_f32_e32 v8, v135, v137
	s_waitcnt lgkmcnt(2)
	v_fmac_f32_e32 v8, v138, v146
	v_fmac_f32_e32 v8, v139, v147
	s_waitcnt lgkmcnt(0)
	v_fmac_f32_e32 v8, v148, v150
	v_fmac_f32_e32 v8, v149, v151
	s_cbranch_scc1 .LBB0_658
	ds_read_b32 v5, v7 offset:49648
	s_mov_b32 s2, 0x3fb8aa3b
	v_mul_f32_e32 v8, v3, v8
	s_waitcnt lgkmcnt(0)
	v_sub_f32_e32 v5, v2, v5
	v_mul_f32_e32 v7, 0x3fb8aa3b, v5
	v_fma_f32 v9, v5, s2, -v7
	v_rndne_f32_e32 v10, v7
	v_fmac_f32_e32 v9, 0x32a5705f, v5
	v_sub_f32_e32 v7, v7, v10
	v_add_f32_e32 v7, v7, v9
	v_cvt_i32_f32_e32 v10, v10
	v_exp_f32_e32 v7, v7
	s_mov_b32 s2, 0xc2ce8ed0
	v_cmp_ngt_f32_e32 vcc, s2, v5
	s_mov_b32 s2, 0x42b17218
	v_ldexp_f32 v7, v7, v10
	v_cndmask_b32_e32 v7, 0, v7, vcc
	v_cmp_nlt_f32_e32 vcc, s2, v5
	s_nop 1
	v_cndmask_b32_e32 v5, v187, v7, vcc
	v_mul_f32_e32 v8, v8, v5
